# MLP-up epilogue stores written through (sc1) so the grid barrier after the phase has less dirty L2 to write back
# speedup vs baseline: 1.0006x; 1.0006x over previous
.Lepi1_fast:
	s_add_i32 s23, s22, s62
	v_lshl_add_u32 v184, v226, 2, s23
	ds_read_b128 v[140:143], v184 offset:1024
	ds_read_b128 v[136:139], v184 offset:1040
	ds_read_b128 v[132:135], v184 offset:1536
	ds_read_b128 v[128:131], v184 offset:1552
	s_lshl_b32 s23, s91, 2
	s_add_i32 s23, s22, s23
	v_lshl_add_u32 v152, v157, 2, s23
	ds_read_b32 v144, v152
	ds_read_b32 v146, v152 offset:64
	ds_read_b32 v148, v152 offset:128
	ds_read_b32 v150, v152 offset:192
	ds_read_b32 v176, v152 offset:512
	ds_read_b32 v178, v152 offset:576
	ds_read_b32 v180, v152 offset:640
	ds_read_b32 v182, v152 offset:704
	v_mul_lo_u32 v185, v174, s10
	v_lshl_or_b32 v184, s56, 8, v228
	v_add_lshl_u32 v184, v185, v184, 1
	s_mov_b64 s[22:23], s[78:79]
	s_lshl_b32 s46, s10, 5
	s_waitcnt lgkmcnt(0)
	v_fmamk_f32 v144, v144, 0x3a800000, v214
	v_fmamk_f32 v146, v146, 0x3a800000, v214
	v_fmamk_f32 v148, v148, 0x3a800000, v214
	v_fmamk_f32 v150, v150, 0x3a800000, v214
	v_fmamk_f32 v176, v176, 0x3a800000, v214
	v_fmamk_f32 v178, v178, 0x3a800000, v214
	v_fmamk_f32 v180, v180, 0x3a800000, v214
	v_fmamk_f32 v182, v182, 0x3a800000, v214
	v_rsq_f32_e32 v144, v144
	v_rsq_f32_e32 v146, v146
	v_rsq_f32_e32 v148, v148
	v_rsq_f32_e32 v150, v150
	v_rsq_f32_e32 v176, v176
	v_rsq_f32_e32 v178, v178
	v_rsq_f32_e32 v180, v180
	v_rsq_f32_e32 v182, v182
	v_pk_fma_f32 v[16:17], v[16:17], v[144:145], v[140:141] op_sel_hi:[1,0,1]
	v_pk_fma_f32 v[18:19], v[18:19], v[144:145], v[142:143] op_sel_hi:[1,0,1]
	v_pk_fma_f32 v[28:29], v[28:29], v[144:145], v[136:137] op_sel_hi:[1,0,1]
	v_pk_fma_f32 v[30:31], v[30:31], v[144:145], v[138:139] op_sel_hi:[1,0,1]
	v_max_f32_e32 v16, 0, v16
	v_max_f32_e32 v17, 0, v17
	v_max_f32_e32 v18, 0, v18
	v_max_f32_e32 v19, 0, v19
	v_max_f32_e32 v28, 0, v28
	v_max_f32_e32 v29, 0, v29
	v_max_f32_e32 v30, 0, v30
	v_max_f32_e32 v31, 0, v31
	v_pk_mul_f32 v[16:17], v[16:17], v[16:17]
	v_pk_mul_f32 v[18:19], v[18:19], v[18:19]
	v_pk_mul_f32 v[28:29], v[28:29], v[28:29]
	v_pk_mul_f32 v[30:31], v[30:31], v[30:31]
	v_cvt_pk_bf16_f32 v16, v16, v17
	v_cvt_pk_bf16_f32 v17, v18, v19
	v_cvt_pk_bf16_f32 v18, v28, v29
	v_cvt_pk_bf16_f32 v19, v30, v31
	global_store_dwordx4 v184, v[16:19], s[22:23] sc1
	v_pk_fma_f32 v[24:25], v[24:25], v[144:145], v[132:133] op_sel_hi:[1,0,1]
	v_pk_fma_f32 v[26:27], v[26:27], v[144:145], v[134:135] op_sel_hi:[1,0,1]
	v_pk_fma_f32 v[20:21], v[20:21], v[144:145], v[128:129] op_sel_hi:[1,0,1]
	v_pk_fma_f32 v[22:23], v[22:23], v[144:145], v[130:131] op_sel_hi:[1,0,1]
	v_max_f32_e32 v24, 0, v24
	v_max_f32_e32 v25, 0, v25
	v_max_f32_e32 v26, 0, v26
	v_max_f32_e32 v27, 0, v27
	v_max_f32_e32 v20, 0, v20
	v_max_f32_e32 v21, 0, v21
	v_max_f32_e32 v22, 0, v22
	v_max_f32_e32 v23, 0, v23
	v_pk_mul_f32 v[24:25], v[24:25], v[24:25]
	v_pk_mul_f32 v[26:27], v[26:27], v[26:27]
	v_pk_mul_f32 v[20:21], v[20:21], v[20:21]
	v_pk_mul_f32 v[22:23], v[22:23], v[22:23]
	v_cvt_pk_bf16_f32 v24, v24, v25
	v_cvt_pk_bf16_f32 v25, v26, v27
	v_cvt_pk_bf16_f32 v26, v20, v21
	v_cvt_pk_bf16_f32 v27, v22, v23
	global_store_dwordx4 v184, v[24:27], s[22:23] offset:256 sc1
	s_add_u32 s22, s22, s46
	s_addc_u32 s23, s23, 0
	v_pk_fma_f32 v[12:13], v[12:13], v[146:147], v[140:141] op_sel_hi:[1,0,1]
	v_pk_fma_f32 v[14:15], v[14:15], v[146:147], v[142:143] op_sel_hi:[1,0,1]
	v_pk_fma_f32 v[8:9], v[8:9], v[146:147], v[136:137] op_sel_hi:[1,0,1]
	v_pk_fma_f32 v[10:11], v[10:11], v[146:147], v[138:139] op_sel_hi:[1,0,1]
	v_max_f32_e32 v12, 0, v12
	v_max_f32_e32 v13, 0, v13
	v_max_f32_e32 v14, 0, v14
	v_max_f32_e32 v15, 0, v15
	v_max_f32_e32 v8, 0, v8
	v_max_f32_e32 v9, 0, v9
	v_max_f32_e32 v10, 0, v10
	v_max_f32_e32 v11, 0, v11
	v_pk_mul_f32 v[12:13], v[12:13], v[12:13]
	v_pk_mul_f32 v[14:15], v[14:15], v[14:15]
	v_pk_mul_f32 v[8:9], v[8:9], v[8:9]
	v_pk_mul_f32 v[10:11], v[10:11], v[10:11]
	v_cvt_pk_bf16_f32 v12, v12, v13
	v_cvt_pk_bf16_f32 v13, v14, v15
	v_cvt_pk_bf16_f32 v14, v8, v9
	v_cvt_pk_bf16_f32 v15, v10, v11
	global_store_dwordx4 v184, v[12:15], s[22:23] sc1
	v_pk_fma_f32 v[4:5], v[4:5], v[146:147], v[132:133] op_sel_hi:[1,0,1]
	v_pk_fma_f32 v[6:7], v[6:7], v[146:147], v[134:135] op_sel_hi:[1,0,1]
	v_pk_fma_f32 v[0:1], v[0:1], v[146:147], v[128:129] op_sel_hi:[1,0,1]
	v_pk_fma_f32 v[2:3], v[2:3], v[146:147], v[130:131] op_sel_hi:[1,0,1]
	v_max_f32_e32 v4, 0, v4
	v_max_f32_e32 v5, 0, v5
	v_max_f32_e32 v6, 0, v6
	v_max_f32_e32 v7, 0, v7
	v_max_f32_e32 v0, 0, v0
	v_max_f32_e32 v1, 0, v1
	v_max_f32_e32 v2, 0, v2
	v_max_f32_e32 v3, 0, v3
	v_pk_mul_f32 v[4:5], v[4:5], v[4:5]
	v_pk_mul_f32 v[6:7], v[6:7], v[6:7]
	v_pk_mul_f32 v[0:1], v[0:1], v[0:1]
	v_pk_mul_f32 v[2:3], v[2:3], v[2:3]
	v_cvt_pk_bf16_f32 v4, v4, v5
	v_cvt_pk_bf16_f32 v5, v6, v7
	v_cvt_pk_bf16_f32 v6, v0, v1
	v_cvt_pk_bf16_f32 v7, v2, v3
	global_store_dwordx4 v184, v[4:7], s[22:23] offset:256 sc1
	s_add_u32 s22, s22, s46
	s_addc_u32 s23, s23, 0
	v_pk_fma_f32 v[124:125], v[124:125], v[148:149], v[140:141] op_sel_hi:[1,0,1]
	v_pk_fma_f32 v[126:127], v[126:127], v[148:149], v[142:143] op_sel_hi:[1,0,1]
	v_pk_fma_f32 v[120:121], v[120:121], v[148:149], v[136:137] op_sel_hi:[1,0,1]
	v_pk_fma_f32 v[122:123], v[122:123], v[148:149], v[138:139] op_sel_hi:[1,0,1]
	v_max_f32_e32 v124, 0, v124
	v_max_f32_e32 v125, 0, v125
	v_max_f32_e32 v126, 0, v126
	v_max_f32_e32 v127, 0, v127
	v_max_f32_e32 v120, 0, v120
	v_max_f32_e32 v121, 0, v121
	v_max_f32_e32 v122, 0, v122
	v_max_f32_e32 v123, 0, v123
	v_pk_mul_f32 v[124:125], v[124:125], v[124:125]
	v_pk_mul_f32 v[126:127], v[126:127], v[126:127]
	v_pk_mul_f32 v[120:121], v[120:121], v[120:121]
	v_pk_mul_f32 v[122:123], v[122:123], v[122:123]
	v_cvt_pk_bf16_f32 v124, v124, v125
	v_cvt_pk_bf16_f32 v125, v126, v127
	v_cvt_pk_bf16_f32 v126, v120, v121
	v_cvt_pk_bf16_f32 v127, v122, v123
	global_store_dwordx4 v184, v[124:127], s[22:23] sc1
	v_pk_fma_f32 v[116:117], v[116:117], v[148:149], v[132:133] op_sel_hi:[1,0,1]
	v_pk_fma_f32 v[118:119], v[118:119], v[148:149], v[134:135] op_sel_hi:[1,0,1]
	v_pk_fma_f32 v[112:113], v[112:113], v[148:149], v[128:129] op_sel_hi:[1,0,1]
	v_pk_fma_f32 v[114:115], v[114:115], v[148:149], v[130:131] op_sel_hi:[1,0,1]
	v_max_f32_e32 v116, 0, v116
	v_max_f32_e32 v117, 0, v117
	v_max_f32_e32 v118, 0, v118
	v_max_f32_e32 v119, 0, v119
	v_max_f32_e32 v112, 0, v112
	v_max_f32_e32 v113, 0, v113
	v_max_f32_e32 v114, 0, v114
	v_max_f32_e32 v115, 0, v115
	v_pk_mul_f32 v[116:117], v[116:117], v[116:117]
	v_pk_mul_f32 v[118:119], v[118:119], v[118:119]
	v_pk_mul_f32 v[112:113], v[112:113], v[112:113]
	v_pk_mul_f32 v[114:115], v[114:115], v[114:115]
	v_cvt_pk_bf16_f32 v116, v116, v117
	v_cvt_pk_bf16_f32 v117, v118, v119
	v_cvt_pk_bf16_f32 v118, v112, v113
	v_cvt_pk_bf16_f32 v119, v114, v115
	global_store_dwordx4 v184, v[116:119], s[22:23] offset:256 sc1
	s_add_u32 s22, s22, s46
	s_addc_u32 s23, s23, 0
	v_pk_fma_f32 v[108:109], v[108:109], v[150:151], v[140:141] op_sel_hi:[1,0,1]
	v_pk_fma_f32 v[110:111], v[110:111], v[150:151], v[142:143] op_sel_hi:[1,0,1]
	v_pk_fma_f32 v[104:105], v[104:105], v[150:151], v[136:137] op_sel_hi:[1,0,1]
	v_pk_fma_f32 v[106:107], v[106:107], v[150:151], v[138:139] op_sel_hi:[1,0,1]
	v_max_f32_e32 v108, 0, v108
	v_max_f32_e32 v109, 0, v109
	v_max_f32_e32 v110, 0, v110
	v_max_f32_e32 v111, 0, v111
	v_max_f32_e32 v104, 0, v104
	v_max_f32_e32 v105, 0, v105
	v_max_f32_e32 v106, 0, v106
	v_max_f32_e32 v107, 0, v107
	v_pk_mul_f32 v[108:109], v[108:109], v[108:109]
	v_pk_mul_f32 v[110:111], v[110:111], v[110:111]
	v_pk_mul_f32 v[104:105], v[104:105], v[104:105]
	v_pk_mul_f32 v[106:107], v[106:107], v[106:107]
	v_cvt_pk_bf16_f32 v108, v108, v109
	v_cvt_pk_bf16_f32 v109, v110, v111
	v_cvt_pk_bf16_f32 v110, v104, v105
	v_cvt_pk_bf16_f32 v111, v106, v107
	global_store_dwordx4 v184, v[108:111], s[22:23] sc1
	v_pk_fma_f32 v[100:101], v[100:101], v[150:151], v[132:133] op_sel_hi:[1,0,1]
	v_pk_fma_f32 v[102:103], v[102:103], v[150:151], v[134:135] op_sel_hi:[1,0,1]
	v_pk_fma_f32 v[96:97], v[96:97], v[150:151], v[128:129] op_sel_hi:[1,0,1]
	v_pk_fma_f32 v[98:99], v[98:99], v[150:151], v[130:131] op_sel_hi:[1,0,1]
	v_max_f32_e32 v100, 0, v100
	v_max_f32_e32 v101, 0, v101
	v_max_f32_e32 v102, 0, v102
	v_max_f32_e32 v103, 0, v103
	v_max_f32_e32 v96, 0, v96
	v_max_f32_e32 v97, 0, v97
	v_max_f32_e32 v98, 0, v98
	v_max_f32_e32 v99, 0, v99
	v_pk_mul_f32 v[100:101], v[100:101], v[100:101]
	v_pk_mul_f32 v[102:103], v[102:103], v[102:103]
	v_pk_mul_f32 v[96:97], v[96:97], v[96:97]
	v_pk_mul_f32 v[98:99], v[98:99], v[98:99]
	v_cvt_pk_bf16_f32 v100, v100, v101
	v_cvt_pk_bf16_f32 v101, v102, v103
	v_cvt_pk_bf16_f32 v102, v96, v97
	v_cvt_pk_bf16_f32 v103, v98, v99
	global_store_dwordx4 v184, v[100:103], s[22:23] offset:256 sc1
	s_add_u32 s22, s22, s46
	s_addc_u32 s23, s23, 0
	s_add_u32 s22, s22, s46
	s_addc_u32 s23, s23, 0
	s_add_u32 s22, s22, s46
	s_addc_u32 s23, s23, 0
	s_add_u32 s22, s22, s46
	s_addc_u32 s23, s23, 0
	s_add_u32 s22, s22, s46
	s_addc_u32 s23, s23, 0
	v_pk_fma_f32 v[92:93], v[92:93], v[176:177], v[140:141] op_sel_hi:[1,0,1]
	v_pk_fma_f32 v[94:95], v[94:95], v[176:177], v[142:143] op_sel_hi:[1,0,1]
	v_pk_fma_f32 v[88:89], v[88:89], v[176:177], v[136:137] op_sel_hi:[1,0,1]
	v_pk_fma_f32 v[90:91], v[90:91], v[176:177], v[138:139] op_sel_hi:[1,0,1]
	v_max_f32_e32 v92, 0, v92
	v_max_f32_e32 v93, 0, v93
	v_max_f32_e32 v94, 0, v94
	v_max_f32_e32 v95, 0, v95
	v_max_f32_e32 v88, 0, v88
	v_max_f32_e32 v89, 0, v89
	v_max_f32_e32 v90, 0, v90
	v_max_f32_e32 v91, 0, v91
	v_pk_mul_f32 v[92:93], v[92:93], v[92:93]
	v_pk_mul_f32 v[94:95], v[94:95], v[94:95]
	v_pk_mul_f32 v[88:89], v[88:89], v[88:89]
	v_pk_mul_f32 v[90:91], v[90:91], v[90:91]
	v_cvt_pk_bf16_f32 v92, v92, v93
	v_cvt_pk_bf16_f32 v93, v94, v95
	v_cvt_pk_bf16_f32 v94, v88, v89
	v_cvt_pk_bf16_f32 v95, v90, v91
	global_store_dwordx4 v184, v[92:95], s[22:23] sc1
	v_pk_fma_f32 v[84:85], v[84:85], v[176:177], v[132:133] op_sel_hi:[1,0,1]
	v_pk_fma_f32 v[86:87], v[86:87], v[176:177], v[134:135] op_sel_hi:[1,0,1]
	v_pk_fma_f32 v[80:81], v[80:81], v[176:177], v[128:129] op_sel_hi:[1,0,1]
	v_pk_fma_f32 v[82:83], v[82:83], v[176:177], v[130:131] op_sel_hi:[1,0,1]
	v_max_f32_e32 v84, 0, v84
	v_max_f32_e32 v85, 0, v85
	v_max_f32_e32 v86, 0, v86
	v_max_f32_e32 v87, 0, v87
	v_max_f32_e32 v80, 0, v80
	v_max_f32_e32 v81, 0, v81
	v_max_f32_e32 v82, 0, v82
	v_max_f32_e32 v83, 0, v83
	v_pk_mul_f32 v[84:85], v[84:85], v[84:85]
	v_pk_mul_f32 v[86:87], v[86:87], v[86:87]
	v_pk_mul_f32 v[80:81], v[80:81], v[80:81]
	v_pk_mul_f32 v[82:83], v[82:83], v[82:83]
	v_cvt_pk_bf16_f32 v84, v84, v85
	v_cvt_pk_bf16_f32 v85, v86, v87
	v_cvt_pk_bf16_f32 v86, v80, v81
	v_cvt_pk_bf16_f32 v87, v82, v83
	global_store_dwordx4 v184, v[84:87], s[22:23] offset:256 sc1
	s_add_u32 s22, s22, s46
	s_addc_u32 s23, s23, 0
	v_pk_fma_f32 v[76:77], v[76:77], v[178:179], v[140:141] op_sel_hi:[1,0,1]
	v_pk_fma_f32 v[78:79], v[78:79], v[178:179], v[142:143] op_sel_hi:[1,0,1]
	v_pk_fma_f32 v[72:73], v[72:73], v[178:179], v[136:137] op_sel_hi:[1,0,1]
	v_pk_fma_f32 v[74:75], v[74:75], v[178:179], v[138:139] op_sel_hi:[1,0,1]
	v_max_f32_e32 v76, 0, v76
	v_max_f32_e32 v77, 0, v77
	v_max_f32_e32 v78, 0, v78
	v_max_f32_e32 v79, 0, v79
	v_max_f32_e32 v72, 0, v72
	v_max_f32_e32 v73, 0, v73
	v_max_f32_e32 v74, 0, v74
	v_max_f32_e32 v75, 0, v75
	v_pk_mul_f32 v[76:77], v[76:77], v[76:77]
	v_pk_mul_f32 v[78:79], v[78:79], v[78:79]
	v_pk_mul_f32 v[72:73], v[72:73], v[72:73]
	v_pk_mul_f32 v[74:75], v[74:75], v[74:75]
	v_cvt_pk_bf16_f32 v76, v76, v77
	v_cvt_pk_bf16_f32 v77, v78, v79
	v_cvt_pk_bf16_f32 v78, v72, v73
	v_cvt_pk_bf16_f32 v79, v74, v75
	global_store_dwordx4 v184, v[76:79], s[22:23] sc1
	v_pk_fma_f32 v[68:69], v[68:69], v[178:179], v[132:133] op_sel_hi:[1,0,1]
	v_pk_fma_f32 v[70:71], v[70:71], v[178:179], v[134:135] op_sel_hi:[1,0,1]
	v_pk_fma_f32 v[64:65], v[64:65], v[178:179], v[128:129] op_sel_hi:[1,0,1]
	v_pk_fma_f32 v[66:67], v[66:67], v[178:179], v[130:131] op_sel_hi:[1,0,1]
	v_max_f32_e32 v68, 0, v68
	v_max_f32_e32 v69, 0, v69
	v_max_f32_e32 v70, 0, v70
	v_max_f32_e32 v71, 0, v71
	v_max_f32_e32 v64, 0, v64
	v_max_f32_e32 v65, 0, v65
	v_max_f32_e32 v66, 0, v66
	v_max_f32_e32 v67, 0, v67
	v_pk_mul_f32 v[68:69], v[68:69], v[68:69]
	v_pk_mul_f32 v[70:71], v[70:71], v[70:71]
	v_pk_mul_f32 v[64:65], v[64:65], v[64:65]
	v_pk_mul_f32 v[66:67], v[66:67], v[66:67]
	v_cvt_pk_bf16_f32 v68, v68, v69
	v_cvt_pk_bf16_f32 v69, v70, v71
	v_cvt_pk_bf16_f32 v70, v64, v65
	v_cvt_pk_bf16_f32 v71, v66, v67
	global_store_dwordx4 v184, v[68:71], s[22:23] offset:256 sc1
	s_add_u32 s22, s22, s46
	s_addc_u32 s23, s23, 0
	v_pk_fma_f32 v[60:61], v[60:61], v[180:181], v[140:141] op_sel_hi:[1,0,1]
	v_pk_fma_f32 v[62:63], v[62:63], v[180:181], v[142:143] op_sel_hi:[1,0,1]
	v_pk_fma_f32 v[56:57], v[56:57], v[180:181], v[136:137] op_sel_hi:[1,0,1]
	v_pk_fma_f32 v[58:59], v[58:59], v[180:181], v[138:139] op_sel_hi:[1,0,1]
	v_max_f32_e32 v60, 0, v60
	v_max_f32_e32 v61, 0, v61
	v_max_f32_e32 v62, 0, v62
	v_max_f32_e32 v63, 0, v63
	v_max_f32_e32 v56, 0, v56
	v_max_f32_e32 v57, 0, v57
	v_max_f32_e32 v58, 0, v58
	v_max_f32_e32 v59, 0, v59
	v_pk_mul_f32 v[60:61], v[60:61], v[60:61]
	v_pk_mul_f32 v[62:63], v[62:63], v[62:63]
	v_pk_mul_f32 v[56:57], v[56:57], v[56:57]
	v_pk_mul_f32 v[58:59], v[58:59], v[58:59]
	v_cvt_pk_bf16_f32 v60, v60, v61
	v_cvt_pk_bf16_f32 v61, v62, v63
	v_cvt_pk_bf16_f32 v62, v56, v57
	v_cvt_pk_bf16_f32 v63, v58, v59
	global_store_dwordx4 v184, v[60:63], s[22:23] sc1
	v_pk_fma_f32 v[52:53], v[52:53], v[180:181], v[132:133] op_sel_hi:[1,0,1]
	v_pk_fma_f32 v[54:55], v[54:55], v[180:181], v[134:135] op_sel_hi:[1,0,1]
	v_pk_fma_f32 v[48:49], v[48:49], v[180:181], v[128:129] op_sel_hi:[1,0,1]
	v_pk_fma_f32 v[50:51], v[50:51], v[180:181], v[130:131] op_sel_hi:[1,0,1]
	v_max_f32_e32 v52, 0, v52
	v_max_f32_e32 v53, 0, v53
	v_max_f32_e32 v54, 0, v54
	v_max_f32_e32 v55, 0, v55
	v_max_f32_e32 v48, 0, v48
	v_max_f32_e32 v49, 0, v49
	v_max_f32_e32 v50, 0, v50
	v_max_f32_e32 v51, 0, v51
	v_pk_mul_f32 v[52:53], v[52:53], v[52:53]
	v_pk_mul_f32 v[54:55], v[54:55], v[54:55]
	v_pk_mul_f32 v[48:49], v[48:49], v[48:49]
	v_pk_mul_f32 v[50:51], v[50:51], v[50:51]
	v_cvt_pk_bf16_f32 v52, v52, v53
	v_cvt_pk_bf16_f32 v53, v54, v55
	v_cvt_pk_bf16_f32 v54, v48, v49
	v_cvt_pk_bf16_f32 v55, v50, v51
	global_store_dwordx4 v184, v[52:55], s[22:23] offset:256 sc1
	s_add_u32 s22, s22, s46
	s_addc_u32 s23, s23, 0
	v_pk_fma_f32 v[44:45], v[44:45], v[182:183], v[140:141] op_sel_hi:[1,0,1]
	v_pk_fma_f32 v[46:47], v[46:47], v[182:183], v[142:143] op_sel_hi:[1,0,1]
	v_pk_fma_f32 v[40:41], v[40:41], v[182:183], v[136:137] op_sel_hi:[1,0,1]
	v_pk_fma_f32 v[42:43], v[42:43], v[182:183], v[138:139] op_sel_hi:[1,0,1]
	v_max_f32_e32 v44, 0, v44
	v_max_f32_e32 v45, 0, v45
	v_max_f32_e32 v46, 0, v46
	v_max_f32_e32 v47, 0, v47
	v_max_f32_e32 v40, 0, v40
	v_max_f32_e32 v41, 0, v41
	v_max_f32_e32 v42, 0, v42
	v_max_f32_e32 v43, 0, v43
	v_pk_mul_f32 v[44:45], v[44:45], v[44:45]
	v_pk_mul_f32 v[46:47], v[46:47], v[46:47]
	v_pk_mul_f32 v[40:41], v[40:41], v[40:41]
	v_pk_mul_f32 v[42:43], v[42:43], v[42:43]
	v_cvt_pk_bf16_f32 v44, v44, v45
	v_cvt_pk_bf16_f32 v45, v46, v47
	v_cvt_pk_bf16_f32 v46, v40, v41
	v_cvt_pk_bf16_f32 v47, v42, v43
	global_store_dwordx4 v184, v[44:47], s[22:23] sc1
	v_pk_fma_f32 v[36:37], v[36:37], v[182:183], v[132:133] op_sel_hi:[1,0,1]
	v_pk_fma_f32 v[38:39], v[38:39], v[182:183], v[134:135] op_sel_hi:[1,0,1]
	v_pk_fma_f32 v[32:33], v[32:33], v[182:183], v[128:129] op_sel_hi:[1,0,1]
	v_pk_fma_f32 v[34:35], v[34:35], v[182:183], v[130:131] op_sel_hi:[1,0,1]
	v_max_f32_e32 v36, 0, v36
	v_max_f32_e32 v37, 0, v37
	v_max_f32_e32 v38, 0, v38
	v_max_f32_e32 v39, 0, v39
	v_max_f32_e32 v32, 0, v32
	v_max_f32_e32 v33, 0, v33
	v_max_f32_e32 v34, 0, v34
	v_max_f32_e32 v35, 0, v35
	v_pk_mul_f32 v[36:37], v[36:37], v[36:37]
	v_pk_mul_f32 v[38:39], v[38:39], v[38:39]
	v_pk_mul_f32 v[32:33], v[32:33], v[32:33]
	v_pk_mul_f32 v[34:35], v[34:35], v[34:35]
	v_cvt_pk_bf16_f32 v36, v36, v37
	v_cvt_pk_bf16_f32 v37, v38, v39
	v_cvt_pk_bf16_f32 v38, v32, v33
	v_cvt_pk_bf16_f32 v39, v34, v35
	global_store_dwordx4 v184, v[36:39], s[22:23] offset:256 sc1
	s_branch .LBB0_461
